# P10: row-1 x/y loads issued with row-0 loads at loop top (both rows in flight), on top of fn-resident and G1 peel
# speedup vs baseline: 1.0044x; 1.0044x over previous
.LBB0_968:
	v_cmp_lt_i32_e32 vcc, s6, v146
	s_and_saveexec_b64 s[2:3], vcc
	s_xor_b64 s[2:3], exec, s[2:3]
	v_add_u32_e32 v0, 0xffffc000, v146
	v_mov_b32_e32 v1, v49
	v_lshlrev_b64 v[0:1], 13, v[0:1]
	v_lshl_add_u64 v[4:5], s[14:15], 0, v[0:1]
	v_mov_b32_e32 v147, v49
	s_andn2_saveexec_b64 s[2:3], s[2:3]
	v_ashrrev_i32_e32 v147, 31, v146
	v_lshlrev_b64 v[0:1], 13, v[146:147]
	v_lshl_add_u64 v[4:5], s[12:13], 0, v[0:1]
	s_or_b64 exec, exec, s[2:3]
	v_lshlrev_b64 v[0:1], 12, v[146:147]
	v_lshl_add_u64 v[6:7], v[56:57], 0, v[0:1]
	v_lshl_add_u64 v[0:1], v[4:5], 0, v[48:49]
	global_load_dwordx4 v[44:47], v[0:1], off offset:16 nt
	global_load_dwordx4 v[36:39], v[0:1], off nt
	global_load_dwordx4 v[40:43], v[6:7], off nt
	global_load_dwordx4 v[28:31], v[6:7], off offset:1024 nt
	global_load_dwordx4 v[32:35], v[0:1], off offset:2064 nt
	global_load_dwordx4 v[24:27], v[0:1], off offset:2048 nt
	v_lshl_add_u64 v[8:9], v[4:5], 0, v[60:61]
	global_load_dwordx4 v[20:23], v[8:9], off offset:16 nt
	global_load_dwordx4 v[12:15], v[8:9], off nt
	global_load_dwordx4 v[16:19], v[6:7], off offset:2048 nt
	global_load_dwordx4 v[0:3], v[6:7], off offset:3072 nt
	v_lshl_add_u64 v[66:67], v[4:5], 0, v[64:65]
	global_load_dwordx4 v[8:11], v[66:67], off offset:16 nt
	global_load_dwordx4 v[4:7], v[66:67], off nt
	v_add_u32_e32 v66, s5, v146
	v_cmp_gt_i32_e32 vcc, s4, v66
	s_nop 1
	v_cndmask_b32_e32 v70, v146, v66, vcc
	v_cmp_lt_i32_e32 vcc, s6, v70
	s_and_saveexec_b64 s[2:3], vcc
	s_xor_b64 s[2:3], exec, s[2:3]
	v_add_u32_e32 v68, 0xffffc000, v70
	v_mov_b32_e32 v69, v49
	v_lshlrev_b64 v[68:69], 13, v[68:69]
	v_lshl_add_u64 v[68:69], s[14:15], 0, v[68:69]
	v_mov_b32_e32 v71, v49
	s_andn2_saveexec_b64 s[2:3], s[2:3]
	v_ashrrev_i32_e32 v71, 31, v70
	v_lshlrev_b64 v[68:69], 13, v[70:71]
	v_lshl_add_u64 v[68:69], s[12:13], 0, v[68:69]
	s_or_b64 exec, exec, s[2:3]
	v_lshl_add_u64 v[240:241], v[68:69], 0, v[48:49]
	v_lshlrev_b64 v[242:243], 12, v[70:71]
	v_lshl_add_u64 v[242:243], v[56:57], 0, v[242:243]
	global_load_dwordx4 v[192:195], v[240:241], off offset:16 nt
	global_load_dwordx4 v[196:199], v[240:241], off nt
	global_load_dwordx4 v[200:203], v[242:243], off nt
	global_load_dwordx4 v[204:207], v[242:243], off offset:1024 nt
	global_load_dwordx4 v[208:211], v[240:241], off offset:2064 nt
	global_load_dwordx4 v[212:215], v[240:241], off offset:2048 nt
	v_lshl_add_u64 v[246:247], v[68:69], 0, v[60:61]
	global_load_dwordx4 v[216:219], v[246:247], off offset:16 nt
	global_load_dwordx4 v[220:223], v[246:247], off nt
	global_load_dwordx4 v[224:227], v[242:243], off offset:2048 nt
	global_load_dwordx4 v[228:231], v[242:243], off offset:3072 nt
	v_lshl_add_u64 v[240:241], v[68:69], 0, v[64:65]
	global_load_dwordx4 v[232:235], v[240:241], off offset:16 nt
	global_load_dwordx4 v[236:239], v[240:241], off nt
	s_waitcnt vmcnt(12)
	v_lshlrev_b32_e32 v88, 16, v42
	v_and_b32_e32 v89, 0xffff0000, v42
	v_lshlrev_b32_e32 v42, 16, v43
	v_and_b32_e32 v43, 0xffff0000, v43
	v_pk_add_f32 v[90:91], v[46:47], v[42:43]
	v_lshlrev_b32_e32 v46, 16, v40
	v_and_b32_e32 v47, 0xffff0000, v40
	v_lshlrev_b32_e32 v40, 16, v41
	v_and_b32_e32 v41, 0xffff0000, v41
	v_pk_add_f32 v[94:95], v[38:39], v[40:41]
	v_lshlrev_b32_e32 v40, 16, v30
	v_and_b32_e32 v41, 0xffff0000, v30
	v_lshlrev_b32_e32 v30, 16, v31
	v_and_b32_e32 v31, 0xffff0000, v31
	v_pk_add_f32 v[98:99], v[34:35], v[30:31]
	v_lshlrev_b32_e32 v34, 16, v28
	v_and_b32_e32 v35, 0xffff0000, v28
	v_lshlrev_b32_e32 v28, 16, v29
	v_and_b32_e32 v29, 0xffff0000, v29
	v_pk_add_f32 v[102:103], v[26:27], v[28:29]
	v_lshlrev_b32_e32 v28, 16, v18
	v_and_b32_e32 v29, 0xffff0000, v18
	v_lshlrev_b32_e32 v18, 16, v19
	v_and_b32_e32 v19, 0xffff0000, v19
	v_mov_b64_e32 v[80:81], v[164:165]
	v_mov_b64_e32 v[82:83], v[166:167]
	v_mov_b64_e32 v[84:85], v[160:161]
	v_mov_b64_e32 v[86:87], v[162:163]
	v_pk_add_f32 v[106:107], v[22:23], v[18:19]
	v_lshlrev_b32_e32 v22, 16, v16
	v_and_b32_e32 v23, 0xffff0000, v16
	v_lshlrev_b32_e32 v16, 16, v17
	v_and_b32_e32 v17, 0xffff0000, v17
	v_pk_add_f32 v[92:93], v[36:37], v[46:47]
	v_pk_add_f32 v[110:111], v[14:15], v[16:17]
	v_lshlrev_b32_e32 v16, 16, v2
	v_and_b32_e32 v17, 0xffff0000, v2
	v_lshlrev_b32_e32 v2, 16, v3
	v_and_b32_e32 v3, 0xffff0000, v3
	v_pk_mul_f32 v[36:37], v[92:93], v[92:93]
	v_pk_add_f32 v[114:115], v[10:11], v[2:3]
	v_lshlrev_b32_e32 v10, 16, v0
	v_and_b32_e32 v11, 0xffff0000, v0
	v_lshlrev_b32_e32 v0, 16, v1
	v_and_b32_e32 v1, 0xffff0000, v1
	v_pk_mul_f32 v[38:39], v[94:95], v[94:95]
	v_pk_add_f32 v[118:119], v[6:7], v[0:1]
	v_add_f32_e32 v6, v36, v37
	v_pk_add_f32 v[88:89], v[44:45], v[88:89]
	v_add_f32_e32 v6, v38, v6
	v_pk_mul_f32 v[44:45], v[88:89], v[88:89]
	v_add_f32_e32 v6, v39, v6
	v_add_f32_e32 v6, v44, v6
	v_pk_mul_f32 v[42:43], v[90:91], v[90:91]
	v_add_f32_e32 v6, v45, v6
	v_pk_add_f32 v[100:101], v[24:25], v[34:35]
	v_add_f32_e32 v6, v42, v6
	v_pk_mul_f32 v[24:25], v[100:101], v[100:101]
	v_add_f32_e32 v6, v43, v6
	v_add_f32_e32 v6, v24, v6
	v_pk_mul_f32 v[26:27], v[102:103], v[102:103]
	v_add_f32_e32 v6, v25, v6
	v_pk_add_f32 v[96:97], v[32:33], v[40:41]
	v_add_f32_e32 v6, v26, v6
	v_pk_mul_f32 v[32:33], v[96:97], v[96:97]
	v_add_f32_e32 v6, v27, v6
	v_add_f32_e32 v6, v32, v6
	v_pk_mul_f32 v[30:31], v[98:99], v[98:99]
	v_add_f32_e32 v6, v33, v6
	v_pk_add_f32 v[108:109], v[12:13], v[22:23]
	v_add_f32_e32 v6, v30, v6
	v_pk_mul_f32 v[12:13], v[108:109], v[108:109]
	v_add_f32_e32 v6, v31, v6
	v_add_f32_e32 v6, v12, v6
	v_pk_mul_f32 v[14:15], v[110:111], v[110:111]
	v_add_f32_e32 v6, v13, v6
	v_pk_add_f32 v[104:105], v[20:21], v[28:29]
	v_add_f32_e32 v6, v14, v6
	v_pk_mul_f32 v[20:21], v[104:105], v[104:105]
	v_add_f32_e32 v6, v15, v6
	v_add_f32_e32 v6, v20, v6
	v_pk_mul_f32 v[18:19], v[106:107], v[106:107]
	v_add_f32_e32 v6, v21, v6
	v_pk_add_f32 v[116:117], v[4:5], v[10:11]
	v_add_f32_e32 v6, v18, v6
	v_pk_mul_f32 v[4:5], v[116:117], v[116:117]
	v_add_f32_e32 v6, v19, v6
	v_add_f32_e32 v4, v4, v6
	v_pk_mul_f32 v[0:1], v[118:119], v[118:119]
	v_add_f32_e32 v4, v5, v4
	v_pk_add_f32 v[112:113], v[8:9], v[16:17]
	v_add_f32_e32 v0, v0, v4
	v_pk_mul_f32 v[8:9], v[112:113], v[112:113]
	v_add_f32_e32 v0, v1, v0
	v_add_f32_e32 v0, v8, v0
	v_pk_mul_f32 v[2:3], v[114:115], v[114:115]
	v_add_f32_e32 v0, v9, v0
	v_add_f32_e32 v0, v2, v0
	v_add_f32_e32 v0, v3, v0
	ds_bpermute_b32 v1, v72, v0
	v_mov_b32_e32 v59, v49
	v_mov_b32_e32 v63, v49
	v_lshl_add_u64 v[6:7], v[68:69], 0, v[58:59]
	s_waitcnt lgkmcnt(0)
	v_add_f32_e32 v2, v0, v1
	ds_bpermute_b32 v3, v73, v2
	v_lshlrev_b64 v[0:1], 12, v[70:71]
	v_lshl_add_u64 v[4:5], v[56:57], 0, v[0:1]
	v_lshl_add_u64 v[0:1], v[68:69], 0, v[48:49]
	v_lshl_add_u64 v[68:69], v[68:69], 0, v[62:63]
	s_waitcnt lgkmcnt(0)
	v_add_f32_e32 v2, v2, v3
	ds_bpermute_b32 v3, v74, v2
	s_waitcnt lgkmcnt(0)
	v_add_f32_e32 v2, v2, v3
	ds_bpermute_b32 v3, v75, v2
	s_waitcnt lgkmcnt(0)
	v_add_f32_e32 v8, v2, v3
	ds_bpermute_b32 v9, v76, v8
	s_waitcnt lgkmcnt(0)
	v_add_f32_e32 v67, v8, v9
	ds_bpermute_b32 v70, v77, v67
	s_waitcnt lgkmcnt(0)
	v_add_f32_e32 v67, v67, v70
	v_fmamk_f32 v67, v67, 0x3a000000, v78
	v_mul_f32_e32 v68, 0x4b800000, v67
	v_cmp_gt_f32_e32 vcc, s7, v67
	s_nop 1
	v_cndmask_b32_e32 v67, v67, v68, vcc
	v_rsq_f32_e32 v67, v67
	v_lshlrev_b64 v[68:69], 13, v[146:147]
	v_lshl_add_u64 v[120:121], s[54:55], 0, v[68:69]
	v_lshl_add_u64 v[122:123], v[120:121], 0, v[48:49]
	v_mul_f32_e32 v68, 0x45800000, v67
	v_cndmask_b32_e32 v124, v67, v68, vcc
	v_pk_mul_f32 v[68:69], v[92:93], v[124:125] op_sel_hi:[1,0]
	v_pk_mul_f32 v[70:71], v[94:95], v[124:125] op_sel_hi:[1,0]
	v_pk_mul_f32 v[68:69], v[84:85], v[68:69]
	v_pk_mul_f32 v[70:71], v[86:87], v[70:71]
	v_pk_mul_f32 v[84:85], v[88:89], v[124:125] op_sel_hi:[1,0]
	v_pk_mul_f32 v[86:87], v[90:91], v[124:125] op_sel_hi:[1,0]
	v_pk_mul_f32 v[80:81], v[80:81], v[84:85]
	v_pk_mul_f32 v[82:83], v[82:83], v[86:87]
	global_store_dwordx4 v[122:123], v[68:71], off nt
	global_store_dwordx4 v[122:123], v[80:83], off offset:16 nt
	s_nop 1
	v_mov_b64_e32 v[68:69], v[168:169]
	v_mov_b64_e32 v[70:71], v[170:171]
	s_nop 0
	v_mov_b64_e32 v[80:81], v[172:173]
	v_mov_b64_e32 v[82:83], v[174:175]
	v_pk_mul_f32 v[84:85], v[102:103], v[124:125] op_sel_hi:[1,0]
	v_pk_mul_f32 v[86:87], v[100:101], v[124:125] op_sel_hi:[1,0]
	v_pk_mul_f32 v[88:89], v[98:99], v[124:125] op_sel_hi:[1,0]
	v_pk_mul_f32 v[90:91], v[96:97], v[124:125] op_sel_hi:[1,0]
	v_pk_mul_f32 v[92:93], v[104:105], v[124:125] op_sel_hi:[1,0]
	v_cmp_gt_i32_e32 vcc, s4, v66
	v_pk_mul_f32 v[68:69], v[68:69], v[86:87]
	v_pk_mul_f32 v[70:71], v[70:71], v[84:85]
	v_pk_mul_f32 v[80:81], v[80:81], v[90:91]
	v_pk_mul_f32 v[82:83], v[82:83], v[88:89]
	global_store_dwordx4 v[122:123], v[68:71], off offset:2048 nt
	global_store_dwordx4 v[122:123], v[80:83], off offset:2064 nt
	s_nop 1
	v_mov_b64_e32 v[68:69], v[176:177]
	v_mov_b64_e32 v[70:71], v[178:179]
	s_nop 0
	v_mov_b64_e32 v[80:81], v[180:181]
	v_mov_b64_e32 v[82:83], v[182:183]
	v_pk_mul_f32 v[86:87], v[110:111], v[124:125] op_sel_hi:[1,0]
	v_pk_mul_f32 v[88:89], v[108:109], v[124:125] op_sel_hi:[1,0]
	v_lshl_add_u64 v[84:85], v[120:121], 0, v[58:59]
	v_pk_mul_f32 v[90:91], v[106:107], v[124:125] op_sel_hi:[1,0]
	v_pk_mul_f32 v[68:69], v[68:69], v[88:89]
	v_pk_mul_f32 v[70:71], v[70:71], v[86:87]
	v_pk_mul_f32 v[80:81], v[92:93], v[80:81]
	v_pk_mul_f32 v[82:83], v[90:91], v[82:83]
	global_store_dwordx4 v[84:85], v[68:71], off nt
	global_store_dwordx4 v[84:85], v[80:83], off offset:16 nt
	s_nop 1
	v_mov_b64_e32 v[68:69], v[184:185]
	v_mov_b64_e32 v[70:71], v[186:187]
	s_nop 0
	v_mov_b64_e32 v[80:81], v[188:189]
	v_mov_b64_e32 v[82:83], v[190:191]
	v_pk_mul_f32 v[86:87], v[118:119], v[124:125] op_sel_hi:[1,0]
	v_pk_mul_f32 v[88:89], v[116:117], v[124:125] op_sel_hi:[1,0]
	v_lshl_add_u64 v[84:85], v[120:121], 0, v[62:63]
	v_pk_mul_f32 v[90:91], v[114:115], v[124:125] op_sel_hi:[1,0]
	v_pk_mul_f32 v[92:93], v[112:113], v[124:125] op_sel_hi:[1,0]
	v_pk_mul_f32 v[68:69], v[88:89], v[68:69]
	v_pk_mul_f32 v[70:71], v[86:87], v[70:71]
	v_pk_mul_f32 v[80:81], v[92:93], v[80:81]
	v_pk_mul_f32 v[82:83], v[90:91], v[82:83]
	global_store_dwordx4 v[84:85], v[68:71], off nt
	global_store_dwordx4 v[84:85], v[80:83], off offset:16 nt
	s_and_saveexec_b64 s[2:3], vcc
	s_cbranch_execz .LBB0_967
	s_waitcnt vmcnt(8)
	v_mov_b64_e32 v[68:69], v[164:165]
	v_mov_b64_e32 v[70:71], v[166:167]
	v_mov_b64_e32 v[80:81], v[160:161]
	v_mov_b64_e32 v[82:83], v[162:163]
	v_lshlrev_b32_e32 v86, 16, v200
	v_and_b32_e32 v87, 0xffff0000, v200
	v_pk_add_f32 v[36:37], v[196:197], v[86:87]
	v_lshlrev_b32_e32 v40, 16, v201
	v_and_b32_e32 v41, 0xffff0000, v201
	v_pk_mul_f32 v[86:87], v[36:37], v[36:37]
	v_pk_add_f32 v[38:39], v[198:199], v[40:41]
	v_lshlrev_b32_e32 v98, 16, v228
	v_and_b32_e32 v99, 0xffff0000, v228
	v_lshlrev_b32_e32 v0, 16, v229
	v_and_b32_e32 v1, 0xffff0000, v229
	v_lshlrev_b32_e32 v84, 16, v202
	v_and_b32_e32 v85, 0xffff0000, v202
	v_pk_mul_f32 v[40:41], v[38:39], v[38:39]
	v_pk_add_f32 v[100:101], v[238:239], v[0:1]
	v_add_f32_e32 v6, v86, v87
	v_pk_add_f32 v[44:45], v[192:193], v[84:85]
	v_add_f32_e32 v6, v40, v6
	v_pk_mul_f32 v[84:85], v[44:45], v[44:45]
	v_lshlrev_b32_e32 v42, 16, v203
	v_and_b32_e32 v43, 0xffff0000, v203
	v_add_f32_e32 v6, v41, v6
	v_pk_add_f32 v[42:43], v[194:195], v[42:43]
	v_add_f32_e32 v6, v84, v6
	v_pk_mul_f32 v[46:47], v[42:43], v[42:43]
	v_lshlrev_b32_e32 v90, 16, v204
	v_and_b32_e32 v91, 0xffff0000, v204
	v_add_f32_e32 v6, v85, v6
	v_pk_add_f32 v[24:25], v[212:213], v[90:91]
	v_add_f32_e32 v6, v46, v6
	v_pk_mul_f32 v[90:91], v[24:25], v[24:25]
	v_lshlrev_b32_e32 v28, 16, v205
	v_and_b32_e32 v29, 0xffff0000, v205
	v_add_f32_e32 v6, v47, v6
	v_pk_add_f32 v[26:27], v[214:215], v[28:29]
	v_add_f32_e32 v6, v90, v6
	v_lshlrev_b32_e32 v88, 16, v206
	v_and_b32_e32 v89, 0xffff0000, v206
	v_pk_mul_f32 v[28:29], v[26:27], v[26:27]
	v_add_f32_e32 v6, v91, v6
	v_pk_add_f32 v[32:33], v[208:209], v[88:89]
	v_add_f32_e32 v6, v28, v6
	v_pk_mul_f32 v[88:89], v[32:33], v[32:33]
	v_lshlrev_b32_e32 v30, 16, v207
	v_and_b32_e32 v31, 0xffff0000, v207
	v_add_f32_e32 v6, v29, v6
	v_pk_add_f32 v[30:31], v[210:211], v[30:31]
	v_add_f32_e32 v6, v88, v6
	v_pk_mul_f32 v[34:35], v[30:31], v[30:31]
	v_lshlrev_b32_e32 v94, 16, v224
	v_and_b32_e32 v95, 0xffff0000, v224
	v_add_f32_e32 v6, v89, v6
	v_pk_add_f32 v[12:13], v[220:221], v[94:95]
	v_add_f32_e32 v6, v34, v6
	v_pk_mul_f32 v[94:95], v[12:13], v[12:13]
	v_lshlrev_b32_e32 v16, 16, v225
	v_and_b32_e32 v17, 0xffff0000, v225
	v_add_f32_e32 v6, v35, v6
	v_pk_add_f32 v[14:15], v[222:223], v[16:17]
	v_add_f32_e32 v6, v94, v6
	v_lshlrev_b32_e32 v92, 16, v226
	v_and_b32_e32 v93, 0xffff0000, v226
	v_pk_mul_f32 v[16:17], v[14:15], v[14:15]
	v_add_f32_e32 v6, v95, v6
	v_pk_add_f32 v[20:21], v[216:217], v[92:93]
	v_add_f32_e32 v6, v16, v6
	v_pk_mul_f32 v[92:93], v[20:21], v[20:21]
	v_lshlrev_b32_e32 v18, 16, v227
	v_and_b32_e32 v19, 0xffff0000, v227
	v_add_f32_e32 v6, v17, v6
	v_pk_add_f32 v[18:19], v[218:219], v[18:19]
	v_add_f32_e32 v6, v92, v6
	v_pk_mul_f32 v[22:23], v[18:19], v[18:19]
	v_add_f32_e32 v6, v93, v6
	v_pk_add_f32 v[98:99], v[236:237], v[98:99]
	v_add_f32_e32 v6, v22, v6
	v_pk_mul_f32 v[4:5], v[98:99], v[98:99]
	v_add_f32_e32 v6, v23, v6
	v_add_f32_e32 v4, v4, v6
	v_lshlrev_b32_e32 v96, 16, v230
	v_and_b32_e32 v97, 0xffff0000, v230
	v_pk_mul_f32 v[0:1], v[100:101], v[100:101]
	v_add_f32_e32 v4, v5, v4
	v_pk_add_f32 v[8:9], v[232:233], v[96:97]
	v_add_f32_e32 v0, v0, v4
	v_pk_mul_f32 v[96:97], v[8:9], v[8:9]
	v_lshlrev_b32_e32 v2, 16, v231
	v_and_b32_e32 v3, 0xffff0000, v231
	v_add_f32_e32 v0, v1, v0
	v_pk_add_f32 v[10:11], v[234:235], v[2:3]
	v_add_f32_e32 v0, v96, v0
	v_pk_mul_f32 v[2:3], v[10:11], v[10:11]
	v_add_f32_e32 v0, v97, v0
	v_add_f32_e32 v0, v2, v0
	v_add_f32_e32 v0, v3, v0
	ds_bpermute_b32 v1, v72, v0
	v_ashrrev_i32_e32 v67, 31, v66
	s_waitcnt lgkmcnt(0)
	v_add_f32_e32 v0, v0, v1
	ds_bpermute_b32 v1, v73, v0
	s_waitcnt lgkmcnt(0)
	v_add_f32_e32 v0, v0, v1
	ds_bpermute_b32 v1, v74, v0
	s_waitcnt lgkmcnt(0)
	v_add_f32_e32 v0, v0, v1
	ds_bpermute_b32 v1, v75, v0
	s_waitcnt lgkmcnt(0)
	v_add_f32_e32 v0, v0, v1
	ds_bpermute_b32 v1, v76, v0
	s_waitcnt lgkmcnt(0)
	v_add_f32_e32 v0, v0, v1
	ds_bpermute_b32 v1, v77, v0
	s_waitcnt lgkmcnt(0)
	v_add_f32_e32 v0, v0, v1
	v_fmamk_f32 v0, v0, 0x3a000000, v78
	v_mul_f32_e32 v1, 0x4b800000, v0
	v_cmp_gt_f32_e32 vcc, s7, v0
	s_nop 1
	v_cndmask_b32_e32 v0, v0, v1, vcc
	v_rsq_f32_e32 v2, v0
	v_lshlrev_b64 v[0:1], 13, v[66:67]
	v_lshl_add_u64 v[16:17], s[54:55], 0, v[0:1]
	v_lshl_add_u64 v[22:23], v[16:17], 0, v[48:49]
	v_mul_f32_e32 v0, 0x45800000, v2
	v_cndmask_b32_e32 v28, v2, v0, vcc
	v_pk_mul_f32 v[0:1], v[36:37], v[28:29] op_sel_hi:[1,0]
	v_pk_mul_f32 v[2:3], v[38:39], v[28:29] op_sel_hi:[1,0]
	v_pk_mul_f32 v[0:1], v[80:81], v[0:1]
	v_pk_mul_f32 v[2:3], v[82:83], v[2:3]
	v_pk_mul_f32 v[4:5], v[44:45], v[28:29] op_sel_hi:[1,0]
	v_pk_mul_f32 v[6:7], v[42:43], v[28:29] op_sel_hi:[1,0]
	v_pk_mul_f32 v[4:5], v[68:69], v[4:5]
	v_pk_mul_f32 v[6:7], v[70:71], v[6:7]
	global_store_dwordx4 v[22:23], v[0:3], off nt
	global_store_dwordx4 v[22:23], v[4:7], off offset:16 nt
	s_nop 1
	v_mov_b64_e32 v[0:1], v[168:169]
	v_mov_b64_e32 v[2:3], v[170:171]
	s_nop 0
	v_mov_b64_e32 v[4:5], v[172:173]
	v_mov_b64_e32 v[6:7], v[174:175]
	v_pk_mul_f32 v[26:27], v[26:27], v[28:29] op_sel_hi:[1,0]
	v_pk_mul_f32 v[24:25], v[24:25], v[28:29] op_sel_hi:[1,0]
	v_pk_mul_f32 v[30:31], v[30:31], v[28:29] op_sel_hi:[1,0]
	v_pk_mul_f32 v[32:33], v[32:33], v[28:29] op_sel_hi:[1,0]
	v_pk_mul_f32 v[14:15], v[14:15], v[28:29] op_sel_hi:[1,0]
	v_pk_mul_f32 v[12:13], v[12:13], v[28:29] op_sel_hi:[1,0]
	v_pk_mul_f32 v[18:19], v[18:19], v[28:29] op_sel_hi:[1,0]
	v_pk_mul_f32 v[20:21], v[20:21], v[28:29] op_sel_hi:[1,0]
	v_pk_mul_f32 v[10:11], v[10:11], v[28:29] op_sel_hi:[1,0]
	v_pk_mul_f32 v[8:9], v[8:9], v[28:29] op_sel_hi:[1,0]
	v_pk_mul_f32 v[0:1], v[0:1], v[24:25]
	v_pk_mul_f32 v[2:3], v[2:3], v[26:27]
	v_pk_mul_f32 v[4:5], v[4:5], v[32:33]
	v_pk_mul_f32 v[6:7], v[6:7], v[30:31]
	global_store_dwordx4 v[22:23], v[0:3], off offset:2048 nt
	global_store_dwordx4 v[22:23], v[4:7], off offset:2064 nt
	s_nop 1
	v_mov_b64_e32 v[0:1], v[176:177]
	v_mov_b64_e32 v[2:3], v[178:179]
	s_nop 0
	v_mov_b64_e32 v[4:5], v[180:181]
	v_mov_b64_e32 v[6:7], v[182:183]
	v_lshl_add_u64 v[22:23], v[16:17], 0, v[58:59]
	v_pk_mul_f32 v[0:1], v[0:1], v[12:13]
	v_pk_mul_f32 v[2:3], v[2:3], v[14:15]
	v_pk_mul_f32 v[4:5], v[20:21], v[4:5]
	v_pk_mul_f32 v[6:7], v[18:19], v[6:7]
	global_store_dwordx4 v[22:23], v[0:3], off nt
	global_store_dwordx4 v[22:23], v[4:7], off offset:16 nt
	s_nop 1
	v_mov_b64_e32 v[0:1], v[184:185]
	v_mov_b64_e32 v[2:3], v[186:187]
	s_nop 0
	v_mov_b64_e32 v[4:5], v[188:189]
	v_mov_b64_e32 v[6:7], v[190:191]
	v_lshl_add_u64 v[12:13], v[16:17], 0, v[62:63]
	v_pk_mul_f32 v[14:15], v[100:101], v[28:29] op_sel_hi:[1,0]
	v_pk_mul_f32 v[16:17], v[98:99], v[28:29] op_sel_hi:[1,0]
	v_pk_mul_f32 v[2:3], v[14:15], v[2:3]
	v_pk_mul_f32 v[0:1], v[16:17], v[0:1]
	v_pk_mul_f32 v[4:5], v[8:9], v[4:5]
	v_pk_mul_f32 v[6:7], v[10:11], v[6:7]
	global_store_dwordx4 v[12:13], v[0:3], off nt
	global_store_dwordx4 v[12:13], v[4:7], off offset:16 nt
	s_branch .LBB0_967
